# v27b + RWKV chunk loop: next-chunk staging moved to the first barrier interval, transposed staging written as dwords (permlane32 swap), last-interval LDS reads issued together before the four MFMAs
# speedup vs baseline: 1.0046x; 1.0046x over previous
; #define LAS __attribute__((address_space(3)))
; __device__ __forceinline__ void lds_barrier() { asm volatile("s_waitcnt lgkmcnt(0)" ::: "memory"); __builtin_amdgcn_s_barrier(); asm volatile("" ::: "memory"); }
; __device__ __forceinline__ void rwkv_chunk_item(const P& p, const Ctx& c, int seg, int w, bool save) {
;     ...
;     auto gload = [&](int ch, int tidv) { const int t = tidv >> 5, j0 = (tidv & 31) * 2; const size_t go = ((size_t)b * SEGT + ch * 16 + t) * DMIX + hh * 64 + j0;
;         ga = *(const unsigned*)(SA + go); gb = *(const unsigned*)(SB + go); gk = *(const unsigned*)(SK + go); gr = *(const unsigned*)(SR + go); gv = *(const unsigned*)(SV + go);
;         if (tidv < 64) gg = GTB[((size_t)(b * 32 + ch) * 24 + hh) * 64 + tidv]; };
;     auto lstore = [&](int pb, int tidv) { const int t = tidv >> 5, j0 = (tidv & 31) * 2;
;         LAS bf16_t* EA = (LAS bf16_t*)(OB + pb * OPB + O_EA); LAS bf16_t* EB = (LAS bf16_t*)(OB + pb * OPB + O_EB); LAS bf16_t* EBT = (LAS bf16_t*)(OB + pb * OPB + O_EBT);
;         LAS bf16_t* UV = (LAS bf16_t*)(OB + pb * OPB + O_UV); LAS float* GT = (LAS float*)(OB + pb * OPB + O_GT);
;         *(LAS unsigned*)(EA + t * 72 + j0) = ga; *(LAS unsigned*)(EA + (16 + t) * 72 + j0) = gr;
;         *(LAS unsigned*)(EB + t * 72 + j0) = gb; *(LAS unsigned*)(EB + (16 + t) * 72 + j0) = gk;
;         EBT[j0 * 40 + t] = (bf16_t)(gb & 0xFFFFu); EBT[(j0 + 1) * 40 + t] = (bf16_t)(gb >> 16); EBT[j0 * 40 + 16 + t] = (bf16_t)(gk & 0xFFFFu); EBT[(j0 + 1) * 40 + 16 + t] = (bf16_t)(gk >> 16);
;         UV[j0 * 40 + 16 + t] = (bf16_t)(gv & 0xFFFFu); UV[(j0 + 1) * 40 + 16 + t] = (bf16_t)(gv >> 16); UV[j0 * 40 + t] = 0; UV[(j0 + 1) * 40 + t] = 0;
;         if (tidv < 64) GT[tidv] = gg; };
;     ...
;         lds_barrier();
;         if (ch + 1 < SEGT / 16) lstore(pb ^ 1, tidv);
;         if (ch + 2 < SEGT / 16) gload(ch + 2, tidv);
.LBB0_886:
	v_mov_b32_e32 v44, v55
	v_mov_b32_e32 v83, v63
	v_mov_b32_e32 v82, v59
	s_waitcnt lgkmcnt(0)
	s_barrier
	s_cmp_eq_u32 s86, 31
	s_cbranch_scc1 .Lrw_nostage
	v_ashrrev_i32_e32 v46, 5, v44
	v_lshlrev_b32_e32 v45, 1, v44
	v_cmp_gt_i32_e64 s[2:3], 64, v44
	s_and_b32 s78, s86, 1
	s_xor_b32 s78, s78, 1
	v_and_b32_e32 v47, 62, v45
	s_mulk_i32 s78, 0x5c00
	s_add_i32 s89, s78, 0
	v_mul_lo_u32 v48, v46, s63
	v_lshlrev_b32_e32 v49, 1, v47
	v_mad_u32_u24 v47, v47, 40, v46
	v_add3_u32 v48, s89, v48, v49
	v_lshl_add_u32 v47, v47, 1, s89
	s_waitcnt vmcnt(0)
	ds_write2st64_b32 v48, v71, v76 offset1:9
	ds_write2st64_b32 v48, v74, v75 offset0:18 offset1:27
	v_bfe_u32 v104, v44, 5, 1
	v_cmp_ne_u32_e32 vcc, 0, v104
	v_mov_b32_e32 v105, 0x5040100
	v_mov_b32_e32 v106, 0x7060302
	v_mul_u32_u24_e32 v104, 0x4e, v104
	v_cndmask_b32_e32 v105, v105, v106, vcc
	v_add_u32_e32 v104, v47, v104
	v_mov_b32_e32 v106, v74
	v_mov_b32_e32 v107, v74
	s_nop 1
	v_permlane32_swap_b32_e32 v106, v107
	v_perm_b32 v108, v107, v106, v105
	ds_write_b32 v104, v108 offset:9216
	v_mov_b32_e32 v106, v75
	v_mov_b32_e32 v107, v75
	s_nop 1
	v_permlane32_swap_b32_e32 v106, v107
	v_perm_b32 v108, v107, v106, v105
	ds_write_b32 v104, v108 offset:9248
	v_mov_b32_e32 v106, v79
	v_mov_b32_e32 v107, v79
	s_nop 1
	v_permlane32_swap_b32_e32 v106, v107
	v_perm_b32 v108, v107, v106, v105
	ds_write_b32 v104, v108 offset:14368
	ds_write_b32 v104, v5 offset:14336
	s_and_saveexec_b64 s[78:79], s[2:3]
	v_lshl_add_u32 v47, v44, 2, s89
	ds_write_b32 v47, v27 offset:23296
	s_or_b64 exec, exec, s[78:79]
	s_cmp_gt_u32 s86, 29
	s_cbranch_scc1 .Lrw_nostage
	v_ashrrev_i32_e32 v47, 31, v46
	v_lshl_add_u64 v[46:47], s[76:77], 0, v[46:47]
	v_mov_b64_e32 v[48:49], s[14:15]
	v_mad_u64_u32 v[48:49], s[2:3], v46, s58, v[48:49]
	v_mov_b32_e32 v46, v49
	v_mad_u64_u32 v[46:47], s[2:3], v47, s58, v[46:47]
	v_and_or_b32 v48, v45, 62, v48
	v_mov_b32_e32 v49, v46
	v_lshlrev_b64 v[46:47], 1, v[48:49]
	v_lshl_add_u64 v[48:49], s[16:17], 0, v[46:47]
	global_load_dword v71, v[48:49], off
	v_lshl_add_u64 v[48:49], s[26:27], 0, v[46:47]
	global_load_dword v74, v[48:49], off
	v_lshl_add_u64 v[48:49], s[20:21], 0, v[46:47]
	global_load_dword v75, v[48:49], off
	v_lshl_add_u64 v[48:49], s[30:31], 0, v[46:47]
	v_lshl_add_u64 v[46:47], s[24:25], 0, v[46:47]
	global_load_dword v76, v[48:49], off
	global_load_dword v79, v[46:47], off
	v_cmp_gt_i32_e32 vcc, 64, v44
	s_and_saveexec_b64 s[2:3], vcc
	s_cbranch_execz .Lrw_gg_done
	s_add_i32 s78, s85, s86
	s_mul_hi_i32 s79, s78, 24
	s_mul_i32 s78, s78, 24
	s_add_u32 s78, s78, s46
	s_addc_u32 s79, s79, s47
	s_lshl_b64 s[78:79], s[78:79], 8
	s_add_u32 s78, s81, s78
	v_ashrrev_i32_e32 v45, 31, v44
	s_addc_u32 s79, s82, s79
	v_lshl_add_u64 v[44:45], v[44:45], 2, s[78:79]
	global_load_dword v27, v[44:45], off

; #define LAS __attribute__((address_space(3)))
; __device__ __forceinline__ unsigned pk2(float lo, float hi) { const bf2_t r = __builtin_convertvector((f32x2){lo, hi}, bf2_t); unsigned u; __builtin_memcpy(&u, &r, 4); return u; }
; __device__ __forceinline__ float bflo(unsigned u) { return __uint_as_float(u << 16); }
; __device__ __forceinline__ float bfhi(unsigned u) { return __uint_as_float(u & 0xFFFF0000u); }
; __device__ __forceinline__ float siluf_(float x) { return x * frcp(1.0f + __expf(-x)); }
; __device__ __forceinline__ void rwkv_chunk_item(const P& p, const Ctx& c, int seg, int w, bool save) {
;     ...
;     auto efinish = [&](int ch) { const f32x4 o4 = *(const LAS f32x4*)(YB + et * 68 + eg * 4);
;         float s1 = (o4[0] + o4[1]) + (o4[2] + o4[3]), s2 = (o4[0] * o4[0] + o4[1] * o4[1]) + (o4[2] * o4[2] + o4[3] * o4[3]);
;         s1 = dpp_add<0xB1>(s1); s2 = dpp_add<0xB1>(s2); s1 = dpp_add<0x4E>(s1); s2 = dpp_add<0x4E>(s2); s1 = dpp_add<0x141>(s1); s2 = dpp_add<0x141>(s2); s1 = dpp_add<0x140>(s1); s2 = dpp_add<0x140>(s2);
;         const float mean = s1 * (1.0f / 64.0f), var = fmaxf(s2 * (1.0f / 64.0f) - mean * mean, 0.f), rs = rsqrtf(var + 64e-5f);
;         const float gg[4] = {bflo(e_g.x), bfhi(e_g.x), bflo(e_g.y), bfhi(e_g.y)}, vv[4] = {bflo(e_v.x), bfhi(e_v.x), bflo(e_v.y), bfhi(e_v.y)}, zz[4] = {bflo(e_z.x), bfhi(e_z.x), bflo(e_z.y), bfhi(e_z.y)};
;         float y[4];
; #pragma unroll
;         for (int j = 0; j < 4; ++j) y[j] = ((o4[j] - mean) * rs * elg[j] + elb[j] + e_rkr * vv[j]) * gg[j] * siluf_(zz[j]);
;         *(u32x2*)(Y + ((size_t)b * SEGT + ch * 16 + et) * DIN + ech) = (u32x2){pk2(y[0], y[1]), pk2(y[2], y[3])}; };
;     ...
;         if (c.wv < 4 && ch > 0) efinish(ch - 1);
.Lrw_nostage:
	s_cmp_eq_u32 s86, 0
	s_cselect_b64 s[2:3], -1, 0
	s_xor_b64 s[4:5], s[6:7], -1
	s_or_b64 s[2:3], s[4:5], s[2:3]
	s_and_b64 vcc, exec, s[2:3]
	s_cbranch_vccnz .LBB0_888
	v_add_u32_e32 v22, v77, v78
	ds_read_b128 v[22:25], v22 offset:60672
	s_mov_b32 s2, 0x3c800000
	v_lshlrev_b32_e32 v56, 16, v42
	v_and_b32_e32 v57, 0xffff0000, v42
	s_waitcnt lgkmcnt(0)
	v_mul_f32_e32 v46, v22, v22
	v_mul_f32_e32 v48, v23, v23
	v_mul_f32_e32 v50, v24, v24
	v_mul_f32_e32 v52, v25, v25
	v_mov_b32_e32 v47, v22
	v_mov_b32_e32 v49, v23
	v_mov_b32_e32 v51, v24
	v_mov_b32_e32 v53, v25
	v_pk_add_f32 v[46:47], v[46:47], v[48:49]
	v_pk_add_f32 v[48:49], v[50:51], v[52:53]
	v_lshlrev_b32_e32 v52, 16, v40
	v_pk_add_f32 v[46:47], v[46:47], v[48:49]
	v_and_b32_e32 v53, 0xffff0000, v40
	v_lshlrev_b32_e32 v50, 16, v38
	v_mov_b32_dpp v49, v47 quad_perm:[1,0,3,2] row_mask:0xf bank_mask:0xf bound_ctrl:1
	v_mov_b32_dpp v48, v46 quad_perm:[1,0,3,2] row_mask:0xf bank_mask:0xf bound_ctrl:1
	v_pk_add_f32 v[46:47], v[46:47], v[48:49]
	v_and_b32_e32 v51, 0xffff0000, v38
	s_nop 0
	v_mov_b32_dpp v49, v47 quad_perm:[2,3,0,1] row_mask:0xf bank_mask:0xf bound_ctrl:1
	v_mov_b32_dpp v48, v46 quad_perm:[2,3,0,1] row_mask:0xf bank_mask:0xf bound_ctrl:1
	v_pk_add_f32 v[46:47], v[46:47], v[48:49]
	s_nop 1
	v_mov_b32_dpp v49, v47 row_half_mirror row_mask:0xf bank_mask:0xf bound_ctrl:1
	v_mov_b32_dpp v48, v46 row_half_mirror row_mask:0xf bank_mask:0xf bound_ctrl:1
	v_pk_add_f32 v[46:47], v[46:47], v[48:49]
	s_nop 1
	v_mov_b32_dpp v49, v47 row_mirror row_mask:0xf bank_mask:0xf bound_ctrl:1
	v_mov_b32_dpp v48, v46 row_mirror row_mask:0xf bank_mask:0xf bound_ctrl:1
	v_pk_add_f32 v[46:47], v[46:47], v[48:49]
	s_nop 0
	v_pk_mul_f32 v[46:47], v[46:47], s[2:3] op_sel_hi:[1,0]
	s_nop 0
	v_fma_f32 v45, -v47, v47, v46
	v_max_f32_e32 v45, 0, v45
	v_add_f32_e32 v45, 0x3a27c5ac, v45
	v_cmp_gt_f32_e32 vcc, s51, v45
	v_mul_f32_e32 v48, 0x4b800000, v45
	v_pk_add_f32 v[22:23], v[22:23], v[46:47] op_sel:[0,1] neg_lo:[0,1] neg_hi:[0,1]
	v_cndmask_b32_e32 v45, v45, v48, vcc
	v_rsq_f32_e32 v45, v45
	v_pk_add_f32 v[24:25], v[24:25], v[46:47] op_sel:[0,1] neg_lo:[0,1] neg_hi:[0,1]
	v_mul_f32_e32 v48, 0x45800000, v45
	v_cndmask_b32_e32 v48, v45, v48, vcc
	v_mul_f32_e32 v45, 0xbfb8aa3b, v56
	v_exp_f32_e32 v45, v45
	v_pk_mul_f32 v[22:23], v[22:23], v[48:49] op_sel_hi:[1,0]
	v_pk_mul_f32 v[24:25], v[24:25], v[48:49] op_sel_hi:[1,0]
	v_pk_fma_f32 v[22:23], v[14:15], v[22:23], v[18:19]
	v_add_f32_e32 v45, 1.0, v45
	v_rcp_f32_e32 v60, v45
	v_mul_f32_e32 v45, 0xbfb8aa3b, v57
	v_exp_f32_e32 v45, v45
	v_pk_fma_f32 v[22:23], v[2:3], v[52:53], v[22:23] op_sel_hi:[0,1,1]
	v_pk_mul_f32 v[22:23], v[22:23], v[50:51]
	v_lshlrev_b32_e32 v52, 16, v41
	v_add_f32_e32 v45, 1.0, v45
	v_rcp_f32_e32 v61, v45
	v_and_b32_e32 v53, 0xffff0000, v41
	v_pk_fma_f32 v[24:25], v[16:17], v[24:25], v[20:21]
	v_pk_mul_f32 v[50:51], v[60:61], v[56:57]
	v_lshlrev_b32_e32 v56, 16, v43
	v_mul_f32_e32 v45, 0xbfb8aa3b, v56
	v_exp_f32_e32 v45, v45
	v_and_b32_e32 v57, 0xffff0000, v43
	v_pk_mul_f32 v[22:23], v[50:51], v[22:23]
	v_lshlrev_b32_e32 v50, 16, v39
	v_add_f32_e32 v45, 1.0, v45
	v_rcp_f32_e32 v60, v45
	v_mul_f32_e32 v45, 0xbfb8aa3b, v57
	v_exp_f32_e32 v45, v45
	v_and_b32_e32 v51, 0xffff0000, v39
	v_pk_fma_f32 v[24:25], v[2:3], v[52:53], v[24:25] op_sel_hi:[0,1,1]
	v_pk_mul_f32 v[24:25], v[24:25], v[50:51]
	v_add_f32_e32 v45, 1.0, v45
	v_rcp_f32_e32 v61, v45
	v_cvt_pk_bf16_f32 v22, v22, v23
	v_pk_mul_f32 v[46:47], v[60:61], v[56:57]
	s_nop 0
	v_pk_mul_f32 v[24:25], v[46:47], v[24:25]
	s_nop 0
	v_cvt_pk_bf16_f32 v23, v24, v25
	v_lshlrev_b64 v[24:25], 12, v[4:5]
	v_lshl_add_u64 v[24:25], v[30:31], 0, v[24:25]
	global_store_dwordx2 v[24:25], v[22:23], off

; __device__ __forceinline__ void lds_barrier() { asm volatile("s_waitcnt lgkmcnt(0)" ::: "memory"); __builtin_amdgcn_s_barrier(); asm volatile("" ::: "memory"); }
; __device__ __forceinline__ void rwkv_chunk_item(const P& p, const Ctx& c, int seg, int w, bool save) {
;     ...
;         lds_barrier();
;         if (ch + 1 < SEGT / 16) lstore(pb ^ 1, tidv);
;         if (ch + 2 < SEGT / 16) gload(ch + 2, tidv);
;         if (c.wv == 0) {
.LBB0_890:
	s_waitcnt lgkmcnt(0)
	s_barrier
	s_cmp_eq_u32 s86, 31
	s_cselect_b64 s[4:5], -1, 0
.LBB0_894:
	s_andn2_b64 vcc, exec, s[70:71]
	s_cbranch_vccnz .LBB0_896

; #define LAS __attribute__((address_space(3)))
; __device__ __forceinline__ bf16_t f2bf(float f) { const __bf16 r = (__bf16)f; bf16_t u; __builtin_memcpy(&u, &r, 2); return u; }
; __device__ __forceinline__ f32x4 mfma16(bf16x8 a, bf16x8 b, f32x4 c) { return __builtin_amdgcn_mfma_f32_16x16x32_bf16(a, b, c, 0, 0, 0); }
; __device__ __forceinline__ void rwkv_chunk_item(const P& p, const Ctx& c, int seg, int w, bool save) {
;     ...
;     auto gtile = [&](int pb, int l15, int quad) {
;         LAS bf16_t* EA = (LAS bf16_t*)(OB + pb * OPB + O_EA); LAS bf16_t* EB = (LAS bf16_t*)(OB + pb * OPB + O_EB);
;         LAS bf16_t* MT1 = (LAS bf16_t*)(OB + pb * OPB + O_MT1); LAS bf16_t* NT = (LAS bf16_t*)(OB + pb * OPB + O_NT); LAS float* MABT = (LAS float*)(OB + pb * OPB + O_MABT);
;         const int sb = c.wv >> 1, tb = c.wv & 1; f32x4 g = (f32x4){0.f, 0.f, 0.f, 0.f};
; #pragma unroll
;         for (int kk = 0; kk < 2; ++kk) g = mfma16(*(const LAS bf16x8*)(EB + (sb * 16 + l15) * 72 + kk * 32 + quad * 8), *(const LAS bf16x8*)(EA + (tb * 16 + l15) * 72 + kk * 32 + quad * 8), g);
; #pragma unroll
;         for (int jj = 0; jj < 4; ++jj) { const int s2 = quad * 4 + jj, tt = l15; const float v = g[jj];
;             if (tb == 0) { const float m = (s2 < tt) ? v : 0.f; if (sb == 0) { MABT[s2 * 20 + tt] = m; MT1[tt * 40 + s2] = 0; } else MT1[tt * 40 + 16 + s2] = f2bf(m); }
;             else { const float m = (s2 <= tt) ? v : 0.f; NT[tt * 40 + sb * 16 + s2] = f2bf(m); } } };
;     ...
;         if (c.wv >= 4) {
;             Zt = mfma16(*(const LAS bf16x8*)(UV + (mtq * 16 + l15) * 40 + quad * 8), *(const LAS bf16x8*)(NT + l15 * 40 + quad * 8), Zt);
;             *(LAS f32x4*)(YB + l15 * 68 + mtq * 16 + quad * 4) = Zt;
;         } else eload(ch);
; #pragma unroll
;         for (int x = 0; x < 2; ++x) { const int ti = c.wv * 2 + x, mt = ti >> 2, nt = ti & 3;
;             S[x] = mfma16(*(const LAS bf16x8*)(UV + (mt * 16 + l15) * 40 + quad * 8), *(const LAS bf16x8*)(EBT + (nt * 16 + l15) * 40 + quad * 8), S[x]);
;             const float gt = GT[nt * 16 + l15];
; #pragma unroll
;             for (int jj = 0; jj < 4; ++jj) S[x][jj] *= gt; }
;         simg(l15, quad);
;         if (c.wv < 4 && ch + 1 < SEGT / 16) gtile(pb ^ 1, l15, quad);
.LBB0_900:
	v_add_u32_e32 v22, s45, v82
	v_lshl_add_u32 v2, v45, 1, s88
	v_mad_u64_u32 v[22:23], s[2:3], v22, s64, v[2:3]
	v_add_u32_e32 v42, s34, v82
	v_mad_u64_u32 v[38:39], s[2:3], v42, s64, v[2:3]
	v_lshl_add_u32 v104, v42, 2, s88
	v_add_u32_e32 v104, 0x5800, v104
	v_add_u32_e32 v105, s66, v82
	v_mad_u64_u32 v[106:107], s[2:3], v105, s64, v[2:3]
	ds_read_b128 v[22:25], v22 offset:14336
	ds_read_b128 v[38:41], v38 offset:9216
	ds_read2_b32 v[42:43], v104 offset0:192 offset1:208
	ds_read_b128 v[104:107], v106 offset:9216
	s_or_b64 s[78:79], s[56:57], s[4:5]
	s_and_b64 vcc, exec, s[78:79]
	s_cbranch_vccnz .Lrw_c_nog
	s_xor_b32 s2, s87, 1
	s_mulk_i32 s2, 0x5c00
	v_add_u32_e32 v124, s67, v82
	v_mul_lo_u32 v124, v124, s63
	v_lshlrev_b32_e32 v125, 1, v45
	v_add_u32_e32 v126, s83, v82
	v_add3_u32 v124, s2, v124, v125
	v_mul_lo_u32 v126, v126, s63
	v_add3_u32 v125, s2, v126, v125
	ds_read_b128 v[108:111], v124 offset:4608
	ds_read_b128 v[112:115], v125
	ds_read_b128 v[116:119], v124 offset:4672
	ds_read_b128 v[120:123], v125 offset:64
.Lrw_c_nog:
	s_waitcnt lgkmcnt(0)
	v_mfma_f32_16x16x32_bf16 v[6:9], v[22:25], v[38:41], v[6:9]
	v_mfma_f32_16x16x32_bf16 v[10:13], v[22:25], v[104:107], v[10:13]
	s_and_b64 vcc, exec, s[78:79]
	s_cbranch_vccnz .Lrw_c_nog2
	v_mfma_f32_16x16x32_bf16 v[108:111], v[108:111], v[112:115], 0
	v_mfma_f32_16x16x32_bf16 v[108:111], v[116:119], v[120:123], v[108:111]
.Lrw_c_nog2:
	v_mov_b32_e32 v2, v43
	v_lshlrev_b32_e32 v38, 2, v83
	s_nop 5
	v_pk_mul_f32 v[6:7], v[42:43], v[6:7] op_sel_hi:[0,1]
	s_nop 1
	v_pk_mul_f32 v[10:11], v[2:3], v[10:11] op_sel_hi:[0,1]
	v_pk_mul_f32 v[12:13], v[2:3], v[12:13] op_sel_hi:[0,1]
	v_add_u32_e32 v2, s45, v38
	v_lshlrev_b32_e32 v22, 1, v82
	v_mul_lo_u32 v2, v2, s63
	v_pk_mul_f32 v[8:9], v[42:43], v[8:9] op_sel_hi:[0,1]
	v_add3_u32 v2, s40, v22, v2
	v_cvt_pk_bf16_f32 v22, v7, s0
	ds_write_b16 v2, v22 offset:47248
	v_cvt_pk_bf16_f32 v22, v8, s0
	ds_write_b16 v2, v22 offset:47392
	v_cvt_pk_bf16_f32 v22, v9, s0
	ds_write_b16 v2, v22 offset:47536
	v_cvt_pk_bf16_f32 v22, v10, s0
	ds_write_b16 v2, v22 offset:47136
	v_cvt_pk_bf16_f32 v22, v11, s0
	ds_write_b16 v2, v22 offset:47280
	v_cvt_pk_bf16_f32 v22, v12, s0
	v_cvt_pk_bf16_f32 v23, v6, s0
	ds_write_b16 v2, v22 offset:47424
	v_cvt_pk_bf16_f32 v22, v13, s0
	s_and_b64 vcc, exec, s[78:79]
	ds_write_b16 v2, v23 offset:47104
	ds_write_b16 v2, v22 offset:47568
	s_cbranch_vccnz .LBB0_929
	s_xor_b32 s2, s87, 1
	s_mulk_i32 s2, 0x5c00
	s_add_i32 s4, s2, 0
	v_mov_b32_e32 v22, v108
	v_mov_b32_e32 v23, v109
	v_mov_b32_e32 v24, v110
	v_mov_b32_e32 v25, v111
	v_add_u32_e32 v39, s4, v84
	v_add_u32_e32 v2, s84, v39
	s_mov_b64 s[2:3], -1
	s_and_b64 vcc, exec, s[72:73]
	v_lshl_add_u32 v40, v38, 1, v2
	s_cbranch_vccz .LBB0_903
	s_nop 3
	v_cvt_pk_bf16_f32 v2, v22, s0
	v_cmp_le_i32_e32 vcc, v38, v82
	s_mov_b64 s[2:3], 0
	s_nop 0
	v_cndmask_b32_e32 v2, 0, v2, vcc
	ds_write_b16 v40, v2 offset:20736

; #define LAS __attribute__((address_space(3)))
; __device__ __forceinline__ unsigned pk2(float lo, float hi) { const bf2_t r = __builtin_convertvector((f32x2){lo, hi}, bf2_t); unsigned u; __builtin_memcpy(&u, &r, 4); return u; }
; __device__ __forceinline__ float bflo(unsigned u) { return __uint_as_float(u << 16); }
; __device__ __forceinline__ float bfhi(unsigned u) { return __uint_as_float(u & 0xFFFF0000u); }
; __device__ __forceinline__ float siluf_(float x) { return x * frcp(1.0f + __expf(-x)); }
; __device__ __forceinline__ void lds_barrier() { asm volatile("s_waitcnt lgkmcnt(0)" ::: "memory"); __builtin_amdgcn_s_barrier(); asm volatile("" ::: "memory"); }
; __device__ __forceinline__ void rwkv_chunk_item(const P& p, const Ctx& c, int seg, int w, bool save) {
;     ...
;     auto efinish = [&](int ch) { const f32x4 o4 = *(const LAS f32x4*)(YB + et * 68 + eg * 4);
;         float s1 = (o4[0] + o4[1]) + (o4[2] + o4[3]), s2 = (o4[0] * o4[0] + o4[1] * o4[1]) + (o4[2] * o4[2] + o4[3] * o4[3]);
;         s1 = dpp_add<0xB1>(s1); s2 = dpp_add<0xB1>(s2); s1 = dpp_add<0x4E>(s1); s2 = dpp_add<0x4E>(s2); s1 = dpp_add<0x141>(s1); s2 = dpp_add<0x141>(s2); s1 = dpp_add<0x140>(s1); s2 = dpp_add<0x140>(s2);
;         const float mean = s1 * (1.0f / 64.0f), var = fmaxf(s2 * (1.0f / 64.0f) - mean * mean, 0.f), rs = rsqrtf(var + 64e-5f);
;         const float gg[4] = {bflo(e_g.x), bfhi(e_g.x), bflo(e_g.y), bfhi(e_g.y)}, vv[4] = {bflo(e_v.x), bfhi(e_v.x), bflo(e_v.y), bfhi(e_v.y)}, zz[4] = {bflo(e_z.x), bfhi(e_z.x), bflo(e_z.y), bfhi(e_z.y)};
;         float y[4];
; #pragma unroll
;         for (int j = 0; j < 4; ++j) y[j] = ((o4[j] - mean) * rs * elg[j] + elb[j] + e_rkr * vv[j]) * gg[j] * siluf_(zz[j]);
;         *(u32x2*)(Y + ((size_t)b * SEGT + ch * 16 + et) * DIN + ech) = (u32x2){pk2(y[0], y[1]), pk2(y[2], y[3])}; };
;     ...
;         simg(l15, quad);
;         if (c.wv < 4 && ch + 1 < SEGT / 16) gtile(pb ^ 1, l15, quad);
;     }
;     lds_barrier();
;     if (c.wv < 4) efinish(SEGT / 16 - 1);
.LBB0_929:
	s_add_i32 s86, s86, 1
	s_add_u32 s76, s76, 16
	s_mov_b64 s[2:3], 0x14000
	s_addc_u32 s77, s77, 0
	v_lshl_add_u64 v[34:35], v[34:35], 0, s[2:3]
	s_mov_b64 s[2:3], 0xc000
	v_add_u32_e32 v4, 16, v4
	v_lshl_add_u64 v[32:33], v[32:33], 0, s[52:53]
	s_cmp_eq_u32 s86, 32
	v_lshl_add_u64 v[36:37], v[36:37], 0, s[2:3]
	s_cbranch_scc1 .LBB0_935
	s_waitcnt vmcnt(3)
	v_mov_b64_e32 v[38:39], v[50:51]
	s_waitcnt vmcnt(2)
	v_mov_b64_e32 v[40:41], v[48:49]
	s_waitcnt vmcnt(1)
	v_mov_b64_e32 v[42:43], v[46:47]
	s_waitcnt vmcnt(0)
	v_mov_b32_e32 v2, v44
	s_branch .LBB0_886
.LBB0_935:
	s_waitcnt lgkmcnt(0)
	s_barrier
	s_and_b64 vcc, exec, s[6:7]
	s_cbranch_vccz .LBB0_822
	v_add_u32_e32 v2, v77, v78
	ds_read_b128 v[22:25], v2 offset:60672
	s_mov_b32 s2, 0x3c800000
	s_waitcnt lgkmcnt(0)
	v_mul_f32_e32 v30, v22, v22
	v_mul_f32_e32 v32, v23, v23
	v_mul_f32_e32 v34, v24, v24
	v_mul_f32_e32 v36, v25, v25
	v_mov_b32_e32 v31, v22
	v_mov_b32_e32 v33, v23
	v_mov_b32_e32 v35, v24
	v_mov_b32_e32 v37, v25
	v_pk_add_f32 v[30:31], v[30:31], v[32:33]
	v_pk_add_f32 v[32:33], v[34:35], v[36:37]
	s_waitcnt vmcnt(1)
	v_lshlrev_b32_e32 v36, 16, v46
	v_pk_add_f32 v[30:31], v[30:31], v[32:33]
	v_and_b32_e32 v37, 0xffff0000, v46
	v_lshlrev_b32_e32 v34, 16, v48
	v_mov_b32_dpp v33, v31 quad_perm:[1,0,3,2] row_mask:0xf bank_mask:0xf bound_ctrl:1
	v_mov_b32_dpp v32, v30 quad_perm:[1,0,3,2] row_mask:0xf bank_mask:0xf bound_ctrl:1
	v_pk_add_f32 v[30:31], v[30:31], v[32:33]
	v_and_b32_e32 v35, 0xffff0000, v48
	s_nop 0
	v_mov_b32_dpp v33, v31 quad_perm:[2,3,0,1] row_mask:0xf bank_mask:0xf bound_ctrl:1
	v_mov_b32_dpp v32, v30 quad_perm:[2,3,0,1] row_mask:0xf bank_mask:0xf bound_ctrl:1
	v_pk_add_f32 v[30:31], v[30:31], v[32:33]
	s_nop 1
	v_mov_b32_dpp v33, v31 row_half_mirror row_mask:0xf bank_mask:0xf bound_ctrl:1
	v_mov_b32_dpp v32, v30 row_half_mirror row_mask:0xf bank_mask:0xf bound_ctrl:1
	v_pk_add_f32 v[30:31], v[30:31], v[32:33]
	s_nop 1
	v_mov_b32_dpp v33, v31 row_mirror row_mask:0xf bank_mask:0xf bound_ctrl:1
	v_mov_b32_dpp v32, v30 row_mirror row_mask:0xf bank_mask:0xf bound_ctrl:1
	v_pk_add_f32 v[30:31], v[30:31], v[32:33]
	v_lshlrev_b32_e32 v32, 16, v50
	v_pk_mul_f32 v[30:31], v[30:31], s[2:3] op_sel_hi:[1,0]
	v_and_b32_e32 v33, 0xffff0000, v50
	v_fma_f32 v2, -v31, v31, v30
	v_max_f32_e32 v2, 0, v2
	v_add_f32_e32 v2, 0x3a27c5ac, v2
	v_cmp_gt_f32_e32 vcc, s51, v2
	v_mul_f32_e32 v4, 0x4b800000, v2
	v_pk_add_f32 v[22:23], v[22:23], v[30:31] op_sel:[0,1] neg_lo:[0,1] neg_hi:[0,1]
	v_cndmask_b32_e32 v2, v2, v4, vcc
	v_rsq_f32_e32 v2, v2
	v_pk_add_f32 v[24:25], v[24:25], v[30:31] op_sel:[0,1] neg_lo:[0,1] neg_hi:[0,1]
	v_mul_f32_e32 v4, 0x45800000, v2
	v_cndmask_b32_e32 v2, v2, v4, vcc
	v_mul_f32_e32 v4, 0xbfb8aa3b, v36
	v_exp_f32_e32 v4, v4
	v_pk_mul_f32 v[22:23], v[22:23], v[2:3] op_sel_hi:[1,0]
	v_pk_mul_f32 v[24:25], v[24:25], v[2:3] op_sel_hi:[1,0]
	v_pk_fma_f32 v[14:15], v[14:15], v[22:23], v[18:19]
	v_add_f32_e32 v4, 1.0, v4
	v_rcp_f32_e32 v38, v4
	v_mul_f32_e32 v4, 0xbfb8aa3b, v37
	v_exp_f32_e32 v4, v4
	s_waitcnt vmcnt(0)
	v_pk_fma_f32 v[14:15], v[44:45], v[34:35], v[14:15] op_sel_hi:[0,1,1]
	v_pk_mul_f32 v[14:15], v[14:15], v[32:33]
	v_lshlrev_b32_e32 v32, 16, v47
	v_add_f32_e32 v4, 1.0, v4
	v_and_b32_e32 v33, 0xffff0000, v47
	v_rcp_f32_e32 v39, v4
	v_mul_f32_e32 v4, 0xbfb8aa3b, v32
	v_mul_f32_e32 v2, 0xbfb8aa3b, v33
	v_exp_f32_e32 v4, v4
	v_exp_f32_e32 v2, v2
	v_pk_mul_f32 v[18:19], v[38:39], v[36:37]
	v_lshlrev_b32_e32 v22, 16, v49
	v_add_f32_e32 v4, 1.0, v4
	v_add_f32_e32 v2, 1.0, v2
	v_rcp_f32_e32 v34, v4
	v_rcp_f32_e32 v35, v2
	v_and_b32_e32 v23, 0xffff0000, v49
	v_pk_fma_f32 v[16:17], v[16:17], v[24:25], v[20:21]
	v_pk_mul_f32 v[14:15], v[18:19], v[14:15]
	v_lshlrev_b32_e32 v18, 16, v51
	v_and_b32_e32 v19, 0xffff0000, v51
	v_pk_fma_f32 v[16:17], v[44:45], v[22:23], v[16:17] op_sel_hi:[0,1,1]
	v_pk_mul_f32 v[16:17], v[16:17], v[18:19]
	v_pk_mul_f32 v[18:19], v[34:35], v[32:33]
	v_lshlrev_b32_e32 v4, 12, v67
	v_pk_mul_f32 v[16:17], v[18:19], v[16:17]
	v_cvt_pk_bf16_f32 v14, v14, v15
	v_cvt_pk_bf16_f32 v15, v16, v17
	v_lshl_add_u64 v[16:17], s[54:55], 0, v[4:5]
	v_lshl_add_u64 v[16:17], v[28:29], 1, v[16:17]
	v_add_co_u32_e32 v16, vcc, 0x1f0000, v16
	s_nop 1
	v_addc_co_u32_e32 v17, vcc, 0, v17, vcc
	global_store_dwordx2 v[16:17], v[14:15], off
	s_branch .LBB0_822
